# phase A rope epilogue: the 24 LDS reads of each half issued up front into dead accumulator registers, counted lgkmcnt waits per pass
# speedup vs baseline: 1.0068x; 1.0019x over previous
; DI unsigned pk2(float lo, float hi) { unsigned r; asm("v_cvt_pk_bf16_f32 %0, %1, %2" : "=v"(r) : "v"(lo), "v"(hi)); return r; }
; DI void phaseA_tile(const P& p, int layer, int mt, int nt, char* lds) {
;     ...
; #pragma unroll
;       for (int pq = 0; pq < 8; ++pq) {
;         const int row = row0 + (half * 8 + pq) * 8 + wm * 4 + fq;
;         const int t = isS ? ((row - NTP) & 63) : (row & 2047);
;         const float* cs = RT + ((size_t)(isS ? PAST + t : t) * rstride + (cc & fmask) * 4) * 2;
;         c0[pq] = *(const f32x4*)cs; c1[pq] = *(const f32x4*)(cs + 4);
;       }
; #pragma unroll
;       for (int pq = 0; pq < 8; ++pq) {
;         const int lr = (half * 8 + pq) * 8 + wm * 4 + fq, row = row0 + lr;
;         const float r = rr[lr];
;         const float* tp = stg + lr * EPS + wn * 64;
;         const f32x4 v = *(const f32x4*)(tp + cc * 4) * r;
;         const f32x4 pv = *(const f32x4*)(tp + (cc ^ pair) * 4) * r;
;         const int bb = isS ? ((row - NTP) >> 6) : (row >> 11);
;         const int t = isS ? ((row - NTP) & 63) : (row & 2047);
;         f32x4 o;
;         o.x = v.x * c0[pq].x + sg * pv.x * c0[pq].y; o.y = v.y * c0[pq].z + sg * pv.y * c0[pq].w;
;         o.z = v.z * c1[pq].x + sg * pv.z * c1[pq].y; o.w = v.w * c1[pq].z + sg * pv.w * c1[pq].w;
;         if (seg < 24) {
;           *(u32x2*)((bf16_t*)(p.ws + W_Q) + (size_t)row * 512 + (seg - 16) * 64 + cc * 4) = u32x2{pk2(o.x * QSCALE, o.y * QSCALE), pk2(o.z * QSCALE, o.w * QSCALE)};
.LBB0_1311:
	v_add_u32_e32 v68, s24, v153
	v_and_b32_e32 v0, s58, v68
	v_or_b32_e32 v66, 0x1000, v0
	v_cndmask_b32_e64 v0, v0, v66, s[38:39]
	v_lshlrev_b64 v[66:67], s59, v[0:1]
	v_lshl_add_u64 v[66:67], v[66:67], 0, v[130:131]
	v_add_u32_e32 v0, 8, v68
	v_lshl_add_u64 v[66:67], v[66:67], 3, s[14:15]
	v_and_b32_e32 v0, s58, v0
	global_load_dwordx4 v[180:183], v[66:67], off offset:16
	global_load_dwordx4 v[122:125], v[66:67], off
	v_or_b32_e32 v66, 0x1000, v0
	v_cndmask_b32_e64 v0, v0, v66, s[38:39]
	v_lshlrev_b64 v[66:67], s59, v[0:1]
	v_lshl_add_u64 v[66:67], v[66:67], 0, v[130:131]
	v_add_u32_e32 v0, 16, v68
	v_lshl_add_u64 v[66:67], v[66:67], 3, s[14:15]
	v_and_b32_e32 v0, s58, v0
	global_load_dwordx4 v[114:117], v[66:67], off offset:16
	global_load_dwordx4 v[118:121], v[66:67], off
	v_or_b32_e32 v66, 0x1000, v0
	v_cndmask_b32_e64 v0, v0, v66, s[38:39]
	v_lshlrev_b64 v[66:67], s59, v[0:1]
	v_lshl_add_u64 v[66:67], v[66:67], 0, v[130:131]
	v_add_u32_e32 v0, 24, v68
	v_lshl_add_u64 v[66:67], v[66:67], 3, s[14:15]
	v_and_b32_e32 v0, s58, v0
	global_load_dwordx4 v[106:109], v[66:67], off offset:16
	global_load_dwordx4 v[110:113], v[66:67], off
	v_or_b32_e32 v66, 0x1000, v0
	v_cndmask_b32_e64 v0, v0, v66, s[38:39]
	v_lshlrev_b64 v[66:67], s59, v[0:1]
	v_lshl_add_u64 v[66:67], v[66:67], 0, v[130:131]
	v_add_u32_e32 v0, 32, v68
	v_lshl_add_u64 v[66:67], v[66:67], 3, s[14:15]
	v_and_b32_e32 v0, s58, v0
	global_load_dwordx4 v[98:101], v[66:67], off offset:16
	global_load_dwordx4 v[102:105], v[66:67], off
	v_or_b32_e32 v66, 0x1000, v0
	v_cndmask_b32_e64 v0, v0, v66, s[38:39]
	v_lshlrev_b64 v[66:67], s59, v[0:1]
	v_lshl_add_u64 v[66:67], v[66:67], 0, v[130:131]
	v_add_u32_e32 v0, 40, v68
	v_lshl_add_u64 v[66:67], v[66:67], 3, s[14:15]
	v_and_b32_e32 v0, s58, v0
	global_load_dwordx4 v[90:93], v[66:67], off offset:16
	global_load_dwordx4 v[94:97], v[66:67], off
	v_or_b32_e32 v66, 0x1000, v0
	v_cndmask_b32_e64 v0, v0, v66, s[38:39]
	v_lshlrev_b64 v[66:67], s59, v[0:1]
	v_lshl_add_u64 v[66:67], v[66:67], 0, v[130:131]
	v_add_u32_e32 v0, 48, v68
	v_lshl_add_u64 v[66:67], v[66:67], 3, s[14:15]
	v_and_b32_e32 v0, s58, v0
	global_load_dwordx4 v[82:85], v[66:67], off offset:16
	global_load_dwordx4 v[86:89], v[66:67], off
	v_or_b32_e32 v66, 0x1000, v0
	v_cndmask_b32_e64 v0, v0, v66, s[38:39]
	v_lshlrev_b64 v[66:67], s59, v[0:1]
	v_lshl_add_u64 v[66:67], v[66:67], 0, v[130:131]
	v_add_u32_e32 v0, 56, v68
	v_lshl_add_u64 v[66:67], v[66:67], 3, s[14:15]
	v_and_b32_e32 v0, s58, v0
	global_load_dwordx4 v[74:77], v[66:67], off offset:16
	global_load_dwordx4 v[78:81], v[66:67], off
	v_or_b32_e32 v66, 0x1000, v0
	v_cndmask_b32_e64 v0, v0, v66, s[38:39]
	v_lshlrev_b64 v[66:67], s59, v[0:1]
	v_lshl_add_u64 v[66:67], v[66:67], 0, v[130:131]
	v_lshl_add_u64 v[70:71], v[66:67], 3, s[14:15]
	global_load_dwordx4 v[66:69], v[70:71], off offset:16
	s_nop 0
	global_load_dwordx4 v[70:73], v[70:71], off
	v_add_u32_e32 v156, s24, v154
	v_mul_lo_u32 v179, v156, s33
	v_add_u32_e32 v145, s57, v179
	v_lshl_add_u32 v157, v156, 2, v173
	v_lshl_add_u32 v146, v126, 2, v145
	v_add_u32_e32 v145, v145, v155
	ds_read_b32 v188, v157
	ds_read_b128 v[2:5], v146
	ds_read_b128 v[6:9], v145
	ds_read_b32 v189, v157 offset:32
	ds_read_b128 v[10:13], v146 offset:4224
	ds_read_b128 v[14:17], v145 offset:4224
	ds_read_b32 v190, v157 offset:64
	ds_read_b128 v[18:21], v146 offset:8448
	ds_read_b128 v[22:25], v145 offset:8448
	ds_read_b32 v191, v157 offset:96
	ds_read_b128 v[26:29], v146 offset:12672
	ds_read_b128 v[30:33], v145 offset:12672
	ds_read_b32 v192, v157 offset:128
	ds_read_b128 v[34:37], v146 offset:16896
	ds_read_b128 v[38:41], v145 offset:16896
	ds_read_b32 v193, v157 offset:160
	ds_read_b128 v[42:45], v146 offset:21120
	ds_read_b128 v[46:49], v145 offset:21120
	ds_read_b32 v194, v157 offset:192
	ds_read_b128 v[50:53], v146 offset:25344
	ds_read_b128 v[54:57], v145 offset:25344
	ds_read_b32 v195, v157 offset:224
	ds_read_b128 v[58:61], v146 offset:29568
	ds_read_b128 v[62:65], v145 offset:29568
	s_waitcnt lgkmcnt(15)
	v_mov_b32_e32 v0, v188
	v_mov_b32_e32 v148, v2
	v_mov_b32_e32 v149, v3
	v_mov_b32_e32 v150, v4
	v_mov_b32_e32 v151, v5
	v_mov_b32_e32 v184, v6
	v_mov_b32_e32 v185, v7
	v_mov_b32_e32 v186, v8
	v_mov_b32_e32 v187, v9
	v_add_u32_e32 v144, s10, v156
	s_and_b64 vcc, exec, s[16:17]
	s_mov_b64 s[0:1], -1
	v_pk_mul_f32 v[148:149], v[148:149], v[0:1] op_sel_hi:[1,0]
	v_pk_mul_f32 v[184:185], v[184:185], v[0:1] op_sel_hi:[1,0]
	v_pk_mul_f32 v[146:147], v[186:187], v[0:1] op_sel_hi:[1,0]
	v_pk_mul_f32 v[184:185], v[128:129], v[184:185]
	v_pk_mul_f32 v[146:147], v[128:129], v[146:147]
	v_pk_mul_f32 v[150:151], v[150:151], v[0:1] op_sel_hi:[1,0]
	s_waitcnt vmcnt(14)
	v_mov_b32_e32 v187, v124
	v_mov_b32_e32 v124, v123
	v_mov_b32_e32 v186, v122
	v_pk_mul_f32 v[122:123], v[124:125], v[184:185]
	v_mov_b32_e32 v125, v182
	v_mov_b32_e32 v182, v181
	v_mov_b32_e32 v124, v180
	v_pk_mul_f32 v[146:147], v[182:183], v[146:147]
	v_pk_fma_f32 v[122:123], v[186:187], v[148:149], v[122:123]
	v_pk_fma_f32 v[124:125], v[124:125], v[150:151], v[146:147]
	s_cbranch_vccz .LBB0_1343
	v_add_u32_e32 v0, 0xffff8000, v144
	v_ashrrev_i32_e32 v180, 6, v0
	v_ashrrev_i32_e32 v146, 11, v144
	v_and_b32_e32 v181, 0x7ff, v144
	s_and_b64 vcc, exec, s[4:5]
	s_cbranch_vccz .LBB0_1332
	s_and_b64 vcc, exec, s[18:19]
	s_cbranch_vccz .LBB0_1329
	s_and_saveexec_b64 s[0:1], s[40:41]
	s_xor_b64 s[0:1], exec, s[0:1]
	s_cbranch_execz .LBB0_1318
	s_and_saveexec_b64 s[24:25], s[42:43]
	s_cbranch_execz .LBB0_1317
	v_ashrrev_i32_e32 v145, 31, v144
	v_lshlrev_b64 v[182:183], 5, v[144:145]
	v_lshl_add_u64 v[182:183], v[140:141], 0, v[182:183]
	s_mov_b32 s26, 0x3d800000
	v_add_co_u32_e32 v182, vcc, 0x15b1d000, v182
	v_pk_mul_f32 v[150:151], v[150:151], s[26:27] op_sel_hi:[1,0]
	v_pk_mul_f32 v[148:149], v[148:149], s[26:27] op_sel_hi:[1,0]
	v_addc_co_u32_e32 v183, vcc, 0, v183, vcc
	global_store_dwordx4 v[182:183], v[148:151], off offset:3968

; DI void phaseA_tile(const P& p, int layer, int mt, int nt, char* lds) {
;     ...
;         const int lr = (half * 8 + pq) * 8 + wm * 4 + fq, row = row0 + lr;
;         const float r = rr[lr];
;         const float* tp = stg + lr * EPS + wn * 64;
;         const f32x4 v = *(const f32x4*)(tp + cc * 4) * r;
;         const f32x4 pv = *(const f32x4*)(tp + (cc ^ pair) * 4) * r;
;         const int bb = isS ? ((row - NTP) >> 6) : (row >> 11);
;         const int t = isS ? ((row - NTP) & 63) : (row & 2047);
;         f32x4 o;
;         o.x = v.x * c0[pq].x + sg * pv.x * c0[pq].y; o.y = v.y * c0[pq].z + sg * pv.y * c0[pq].w;
;         o.z = v.z * c1[pq].x + sg * pv.z * c1[pq].y; o.w = v.w * c1[pq].z + sg * pv.w * c1[pq].w;
.LBB0_1345:
	v_add_u32_e32 v146, 0x1080, v179
	v_add_u32_e32 v0, s57, v146
	v_lshl_add_u32 v122, v126, 2, v0
	v_add_u32_e32 v0, v0, v155
	s_waitcnt lgkmcnt(15)
	v_mov_b32_e32 v184, v189
	v_mov_b32_e32 v148, v10
	v_mov_b32_e32 v149, v11
	v_mov_b32_e32 v150, v12
	v_mov_b32_e32 v151, v13
	v_mov_b32_e32 v180, v14
	v_mov_b32_e32 v181, v15
	v_mov_b32_e32 v182, v16
	v_mov_b32_e32 v183, v17
	v_add_u32_e32 v0, 8, v156
	v_add_u32_e32 v122, s10, v0
	s_mov_b64 s[0:1], -1
	v_pk_mul_f32 v[144:145], v[150:151], v[184:185] op_sel_hi:[1,0]
	v_pk_mul_f32 v[150:151], v[180:181], v[184:185] op_sel_hi:[1,0]
	v_pk_mul_f32 v[124:125], v[148:149], v[184:185] op_sel_hi:[1,0]
	v_pk_mul_f32 v[148:149], v[182:183], v[184:185] op_sel_hi:[1,0]
	s_waitcnt vmcnt(12)
	v_mov_b32_e32 v181, v120
	v_pk_mul_f32 v[150:151], v[128:129], v[150:151]
	v_mov_b32_e32 v120, v119
	v_mov_b32_e32 v180, v118
	v_pk_mul_f32 v[118:119], v[120:121], v[150:151]
	v_mov_b32_e32 v121, v116
	v_pk_mul_f32 v[148:149], v[128:129], v[148:149]
	v_mov_b32_e32 v116, v115
	v_mov_b32_e32 v120, v114
	v_pk_mul_f32 v[114:115], v[116:117], v[148:149]
	v_pk_fma_f32 v[118:119], v[180:181], v[124:125], v[118:119]
	v_pk_fma_f32 v[120:121], v[120:121], v[144:145], v[114:115]
	v_cndmask_b32_e64 v114, 0, 1, s[16:17]
	v_cmp_ne_u32_e64 s[46:47], 1, v114
	v_cndmask_b32_e64 v114, 0, 1, s[4:5]
	s_andn2_b64 vcc, exec, s[16:17]
	v_cmp_ne_u32_e64 s[44:45], 1, v114
	s_cbranch_vccnz .LBB0_1377
	v_add_u32_e32 v114, 0xffff8000, v122
	v_ashrrev_i32_e32 v147, 6, v114
	v_ashrrev_i32_e32 v114, 11, v122
	v_and_b32_e32 v148, 63, v0
	v_and_b32_e32 v149, 0x7ff, v122
	s_and_b64 vcc, exec, s[44:45]
	s_cbranch_vccnz .LBB0_1366
	s_andn2_b64 vcc, exec, s[18:19]
	s_cbranch_vccnz .LBB0_1363
	s_and_saveexec_b64 s[0:1], s[40:41]
	s_xor_b64 s[0:1], exec, s[0:1]
	s_cbranch_execz .LBB0_1352
	s_and_saveexec_b64 s[24:25], s[42:43]
	s_cbranch_execz .LBB0_1351
	v_ashrrev_i32_e32 v123, 31, v122
	v_lshlrev_b64 v[116:117], 5, v[122:123]
	v_lshl_add_u64 v[116:117], v[140:141], 0, v[116:117]
	s_mov_b32 s26, 0x3d800000
	v_add_co_u32_e32 v116, vcc, 0x15b1d000, v116
	v_pk_mul_f32 v[182:183], v[144:145], s[26:27] op_sel_hi:[1,0]
	v_pk_mul_f32 v[180:181], v[124:125], s[26:27] op_sel_hi:[1,0]
	v_addc_co_u32_e32 v117, vcc, 0, v117, vcc
	global_store_dwordx4 v[116:117], v[180:183], off offset:3968

; DI void phaseA_tile(const P& p, int layer, int mt, int nt, char* lds) {
;     ...
;         const int lr = (half * 8 + pq) * 8 + wm * 4 + fq, row = row0 + lr;
;         const float r = rr[lr];
;         const float* tp = stg + lr * EPS + wn * 64;
;         const f32x4 v = *(const f32x4*)(tp + cc * 4) * r;
;         const f32x4 pv = *(const f32x4*)(tp + (cc ^ pair) * 4) * r;
;         const int bb = isS ? ((row - NTP) >> 6) : (row >> 11);
;         const int t = isS ? ((row - NTP) & 63) : (row & 2047);
;         f32x4 o;
;         o.x = v.x * c0[pq].x + sg * pv.x * c0[pq].y; o.y = v.y * c0[pq].z + sg * pv.y * c0[pq].w;
;         o.z = v.z * c1[pq].x + sg * pv.z * c1[pq].y; o.w = v.w * c1[pq].z + sg * pv.w * c1[pq].w;
.LBB0_1379:
	v_add_u32_e32 v120, 0x1080, v146
	v_add_u32_e32 v0, s57, v120
	v_lshl_add_u32 v114, v126, 2, v0
	v_add_u32_e32 v0, v0, v155
	s_waitcnt lgkmcnt(15)
	v_mov_b32_e32 v144, v190
	v_mov_b32_e32 v116, v18
	v_mov_b32_e32 v117, v19
	v_mov_b32_e32 v118, v20
	v_mov_b32_e32 v119, v21
	v_mov_b32_e32 v122, v22
	v_mov_b32_e32 v123, v23
	v_mov_b32_e32 v124, v24
	v_mov_b32_e32 v125, v25
	v_add_u32_e32 v0, 16, v156
	v_add_u32_e32 v114, s10, v0
	s_and_b64 vcc, exec, s[46:47]
	v_pk_mul_f32 v[116:117], v[116:117], v[144:145] op_sel_hi:[1,0]
	v_pk_mul_f32 v[122:123], v[122:123], v[144:145] op_sel_hi:[1,0]
	v_pk_mul_f32 v[118:119], v[118:119], v[144:145] op_sel_hi:[1,0]
	v_pk_mul_f32 v[124:125], v[124:125], v[144:145] op_sel_hi:[1,0]
	s_waitcnt vmcnt(10)
	v_mov_b32_e32 v145, v112
	v_pk_mul_f32 v[122:123], v[128:129], v[122:123]
	v_mov_b32_e32 v112, v111
	v_mov_b32_e32 v144, v110
	v_pk_mul_f32 v[110:111], v[112:113], v[122:123]
	v_mov_b32_e32 v113, v108
	v_pk_mul_f32 v[122:123], v[128:129], v[124:125]
	v_mov_b32_e32 v108, v107
	v_mov_b32_e32 v112, v106
	v_pk_mul_f32 v[106:107], v[108:109], v[122:123]
	v_pk_fma_f32 v[110:111], v[144:145], v[116:117], v[110:111]
	v_pk_fma_f32 v[112:113], v[112:113], v[118:119], v[106:107]
	s_mov_b64 s[0:1], -1
	s_cbranch_vccnz .LBB0_1411
	v_add_u32_e32 v106, 0xffff8000, v114
	v_ashrrev_i32_e32 v121, 6, v106
	v_ashrrev_i32_e32 v106, 11, v114
	v_and_b32_e32 v122, 63, v0
	v_and_b32_e32 v123, 0x7ff, v114
	s_and_b64 vcc, exec, s[44:45]
	s_cbranch_vccnz .LBB0_1400
	s_andn2_b64 vcc, exec, s[18:19]
	s_cbranch_vccnz .LBB0_1397
	s_and_saveexec_b64 s[0:1], s[40:41]
	s_xor_b64 s[0:1], exec, s[0:1]
	s_cbranch_execz .LBB0_1386
	s_and_saveexec_b64 s[24:25], s[42:43]
	s_cbranch_execz .LBB0_1385
	v_ashrrev_i32_e32 v115, 31, v114
	v_lshlrev_b64 v[108:109], 5, v[114:115]
	v_lshl_add_u64 v[108:109], v[140:141], 0, v[108:109]
	s_mov_b32 s26, 0x3d800000
	v_add_co_u32_e32 v108, vcc, 0x15b1d000, v108
	v_pk_mul_f32 v[118:119], v[118:119], s[26:27] op_sel_hi:[1,0]
	v_pk_mul_f32 v[116:117], v[116:117], s[26:27] op_sel_hi:[1,0]
	v_addc_co_u32_e32 v109, vcc, 0, v109, vcc
	global_store_dwordx4 v[108:109], v[116:119], off offset:3968

; DI void phaseA_tile(const P& p, int layer, int mt, int nt, char* lds) {
;     ...
;         const int lr = (half * 8 + pq) * 8 + wm * 4 + fq, row = row0 + lr;
;         const float r = rr[lr];
;         const float* tp = stg + lr * EPS + wn * 64;
;         const f32x4 v = *(const f32x4*)(tp + cc * 4) * r;
;         const f32x4 pv = *(const f32x4*)(tp + (cc ^ pair) * 4) * r;
;         const int bb = isS ? ((row - NTP) >> 6) : (row >> 11);
;         const int t = isS ? ((row - NTP) & 63) : (row & 2047);
;         f32x4 o;
;         o.x = v.x * c0[pq].x + sg * pv.x * c0[pq].y; o.y = v.y * c0[pq].z + sg * pv.y * c0[pq].w;
;         o.z = v.z * c1[pq].x + sg * pv.z * c1[pq].y; o.w = v.w * c1[pq].z + sg * pv.w * c1[pq].w;
.LBB0_1413:
	v_add_u32_e32 v112, 0x1080, v120
	v_add_u32_e32 v0, s57, v112
	v_lshl_add_u32 v106, v126, 2, v0
	v_add_u32_e32 v0, v0, v155
	s_waitcnt lgkmcnt(12)
	v_mov_b32_e32 v118, v191
	v_mov_b32_e32 v108, v26
	v_mov_b32_e32 v109, v27
	v_mov_b32_e32 v110, v28
	v_mov_b32_e32 v111, v29
	v_mov_b32_e32 v114, v30
	v_mov_b32_e32 v115, v31
	v_mov_b32_e32 v116, v32
	v_mov_b32_e32 v117, v33
	v_add_u32_e32 v0, 24, v156
	v_add_u32_e32 v106, s10, v0
	s_and_b64 vcc, exec, s[46:47]
	v_pk_mul_f32 v[108:109], v[108:109], v[118:119] op_sel_hi:[1,0]
	v_pk_mul_f32 v[114:115], v[114:115], v[118:119] op_sel_hi:[1,0]
	v_pk_mul_f32 v[110:111], v[110:111], v[118:119] op_sel_hi:[1,0]
	v_pk_mul_f32 v[116:117], v[116:117], v[118:119] op_sel_hi:[1,0]
	s_waitcnt vmcnt(8)
	v_mov_b32_e32 v119, v104
	v_pk_mul_f32 v[114:115], v[128:129], v[114:115]
	v_mov_b32_e32 v104, v103
	v_mov_b32_e32 v118, v102
	v_pk_mul_f32 v[102:103], v[104:105], v[114:115]
	v_mov_b32_e32 v105, v100
	v_pk_mul_f32 v[114:115], v[128:129], v[116:117]
	v_mov_b32_e32 v100, v99
	v_mov_b32_e32 v104, v98
	v_pk_mul_f32 v[98:99], v[100:101], v[114:115]
	v_pk_fma_f32 v[102:103], v[118:119], v[108:109], v[102:103]
	v_pk_fma_f32 v[104:105], v[104:105], v[110:111], v[98:99]
	s_mov_b64 s[0:1], -1
	s_cbranch_vccnz .LBB0_1445
	v_add_u32_e32 v98, 0xffff8000, v106
	v_ashrrev_i32_e32 v113, 6, v98
	v_ashrrev_i32_e32 v98, 11, v106
	v_and_b32_e32 v114, 63, v0
	v_and_b32_e32 v115, 0x7ff, v106
	s_and_b64 vcc, exec, s[44:45]
	s_cbranch_vccnz .LBB0_1434
	s_andn2_b64 vcc, exec, s[18:19]
	s_cbranch_vccnz .LBB0_1431
	s_and_saveexec_b64 s[0:1], s[40:41]
	s_xor_b64 s[0:1], exec, s[0:1]
	s_cbranch_execz .LBB0_1420
	s_and_saveexec_b64 s[24:25], s[42:43]
	s_cbranch_execz .LBB0_1419
	v_ashrrev_i32_e32 v107, 31, v106
	v_lshlrev_b64 v[100:101], 5, v[106:107]
	v_lshl_add_u64 v[100:101], v[140:141], 0, v[100:101]
	s_mov_b32 s26, 0x3d800000
	v_add_co_u32_e32 v100, vcc, 0x15b1d000, v100
	v_pk_mul_f32 v[110:111], v[110:111], s[26:27] op_sel_hi:[1,0]
	v_pk_mul_f32 v[108:109], v[108:109], s[26:27] op_sel_hi:[1,0]
	v_addc_co_u32_e32 v101, vcc, 0, v101, vcc
	global_store_dwordx4 v[100:101], v[108:111], off offset:3968

; DI void phaseA_tile(const P& p, int layer, int mt, int nt, char* lds) {
;     ...
;         const int lr = (half * 8 + pq) * 8 + wm * 4 + fq, row = row0 + lr;
;         const float r = rr[lr];
;         const float* tp = stg + lr * EPS + wn * 64;
;         const f32x4 v = *(const f32x4*)(tp + cc * 4) * r;
;         const f32x4 pv = *(const f32x4*)(tp + (cc ^ pair) * 4) * r;
;         const int bb = isS ? ((row - NTP) >> 6) : (row >> 11);
;         const int t = isS ? ((row - NTP) & 63) : (row & 2047);
;         f32x4 o;
;         o.x = v.x * c0[pq].x + sg * pv.x * c0[pq].y; o.y = v.y * c0[pq].z + sg * pv.y * c0[pq].w;
;         o.z = v.z * c1[pq].x + sg * pv.z * c1[pq].y; o.w = v.w * c1[pq].z + sg * pv.w * c1[pq].w;
.LBB0_1447:
	v_add_u32_e32 v104, 0x1080, v112
	v_add_u32_e32 v0, s57, v104
	v_lshl_add_u32 v98, v126, 2, v0
	v_add_u32_e32 v0, v0, v155
	s_waitcnt lgkmcnt(9)
	v_mov_b32_e32 v110, v192
	v_mov_b32_e32 v100, v34
	v_mov_b32_e32 v101, v35
	v_mov_b32_e32 v102, v36
	v_mov_b32_e32 v103, v37
	v_mov_b32_e32 v106, v38
	v_mov_b32_e32 v107, v39
	v_mov_b32_e32 v108, v40
	v_mov_b32_e32 v109, v41
	v_add_u32_e32 v0, 32, v156
	v_add_u32_e32 v98, s10, v0
	s_and_b64 vcc, exec, s[46:47]
	v_pk_mul_f32 v[100:101], v[100:101], v[110:111] op_sel_hi:[1,0]
	v_pk_mul_f32 v[106:107], v[106:107], v[110:111] op_sel_hi:[1,0]
	v_pk_mul_f32 v[102:103], v[102:103], v[110:111] op_sel_hi:[1,0]
	v_pk_mul_f32 v[108:109], v[108:109], v[110:111] op_sel_hi:[1,0]
	s_waitcnt vmcnt(6)
	v_mov_b32_e32 v111, v96
	v_pk_mul_f32 v[106:107], v[128:129], v[106:107]
	v_mov_b32_e32 v96, v95
	v_mov_b32_e32 v110, v94
	v_pk_mul_f32 v[94:95], v[96:97], v[106:107]
	v_mov_b32_e32 v97, v92
	v_pk_mul_f32 v[106:107], v[128:129], v[108:109]
	v_mov_b32_e32 v92, v91
	v_mov_b32_e32 v96, v90
	v_pk_mul_f32 v[90:91], v[92:93], v[106:107]
	v_pk_fma_f32 v[94:95], v[110:111], v[100:101], v[94:95]
	v_pk_fma_f32 v[96:97], v[96:97], v[102:103], v[90:91]
	s_mov_b64 s[0:1], -1
	s_cbranch_vccnz .LBB0_1479
	v_add_u32_e32 v90, 0xffff8000, v98
	v_ashrrev_i32_e32 v105, 6, v90
	v_ashrrev_i32_e32 v90, 11, v98
	v_and_b32_e32 v106, 63, v0
	v_and_b32_e32 v107, 0x7ff, v98
	s_and_b64 vcc, exec, s[44:45]
	s_cbranch_vccnz .LBB0_1468
	s_andn2_b64 vcc, exec, s[18:19]
	s_cbranch_vccnz .LBB0_1465
	s_and_saveexec_b64 s[0:1], s[40:41]
	s_xor_b64 s[0:1], exec, s[0:1]
	s_cbranch_execz .LBB0_1454
	s_and_saveexec_b64 s[24:25], s[42:43]
	s_cbranch_execz .LBB0_1453
	v_ashrrev_i32_e32 v99, 31, v98
	v_lshlrev_b64 v[92:93], 5, v[98:99]
	v_lshl_add_u64 v[92:93], v[140:141], 0, v[92:93]
	s_mov_b32 s26, 0x3d800000
	v_add_co_u32_e32 v92, vcc, 0x15b1d000, v92
	v_pk_mul_f32 v[102:103], v[102:103], s[26:27] op_sel_hi:[1,0]
	v_pk_mul_f32 v[100:101], v[100:101], s[26:27] op_sel_hi:[1,0]
	v_addc_co_u32_e32 v93, vcc, 0, v93, vcc
	global_store_dwordx4 v[92:93], v[100:103], off offset:3968

; DI void phaseA_tile(const P& p, int layer, int mt, int nt, char* lds) {
;     ...
;         const int lr = (half * 8 + pq) * 8 + wm * 4 + fq, row = row0 + lr;
;         const float r = rr[lr];
;         const float* tp = stg + lr * EPS + wn * 64;
;         const f32x4 v = *(const f32x4*)(tp + cc * 4) * r;
;         const f32x4 pv = *(const f32x4*)(tp + (cc ^ pair) * 4) * r;
;         const int bb = isS ? ((row - NTP) >> 6) : (row >> 11);
;         const int t = isS ? ((row - NTP) & 63) : (row & 2047);
;         f32x4 o;
;         o.x = v.x * c0[pq].x + sg * pv.x * c0[pq].y; o.y = v.y * c0[pq].z + sg * pv.y * c0[pq].w;
;         o.z = v.z * c1[pq].x + sg * pv.z * c1[pq].y; o.w = v.w * c1[pq].z + sg * pv.w * c1[pq].w;
.LBB0_1481:
	v_add_u32_e32 v96, 0x1080, v104
	v_add_u32_e32 v0, s57, v96
	v_lshl_add_u32 v90, v126, 2, v0
	v_add_u32_e32 v0, v0, v155
	s_waitcnt lgkmcnt(6)
	v_mov_b32_e32 v102, v193
	v_mov_b32_e32 v92, v42
	v_mov_b32_e32 v93, v43
	v_mov_b32_e32 v94, v44
	v_mov_b32_e32 v95, v45
	v_mov_b32_e32 v98, v46
	v_mov_b32_e32 v99, v47
	v_mov_b32_e32 v100, v48
	v_mov_b32_e32 v101, v49
	v_add_u32_e32 v0, 40, v156
	v_add_u32_e32 v90, s10, v0
	s_and_b64 vcc, exec, s[46:47]
	v_pk_mul_f32 v[92:93], v[92:93], v[102:103] op_sel_hi:[1,0]
	v_pk_mul_f32 v[98:99], v[98:99], v[102:103] op_sel_hi:[1,0]
	v_pk_mul_f32 v[94:95], v[94:95], v[102:103] op_sel_hi:[1,0]
	v_pk_mul_f32 v[100:101], v[100:101], v[102:103] op_sel_hi:[1,0]
	s_waitcnt vmcnt(4)
	v_mov_b32_e32 v103, v88
	v_pk_mul_f32 v[98:99], v[128:129], v[98:99]
	v_mov_b32_e32 v88, v87
	v_mov_b32_e32 v102, v86
	v_pk_mul_f32 v[86:87], v[88:89], v[98:99]
	v_mov_b32_e32 v89, v84
	v_pk_mul_f32 v[98:99], v[128:129], v[100:101]
	v_mov_b32_e32 v84, v83
	v_mov_b32_e32 v88, v82
	v_pk_mul_f32 v[82:83], v[84:85], v[98:99]
	v_pk_fma_f32 v[86:87], v[102:103], v[92:93], v[86:87]
	v_pk_fma_f32 v[88:89], v[88:89], v[94:95], v[82:83]
	s_mov_b64 s[0:1], -1
	s_cbranch_vccnz .LBB0_1513
	v_add_u32_e32 v82, 0xffff8000, v90
	v_ashrrev_i32_e32 v97, 6, v82
	v_ashrrev_i32_e32 v82, 11, v90
	v_and_b32_e32 v98, 63, v0
	v_and_b32_e32 v99, 0x7ff, v90
	s_and_b64 vcc, exec, s[44:45]
	s_cbranch_vccnz .LBB0_1502
	s_andn2_b64 vcc, exec, s[18:19]
	s_cbranch_vccnz .LBB0_1499
	s_and_saveexec_b64 s[0:1], s[40:41]
	s_xor_b64 s[0:1], exec, s[0:1]
	s_cbranch_execz .LBB0_1488
	s_and_saveexec_b64 s[24:25], s[42:43]
	s_cbranch_execz .LBB0_1487
	v_ashrrev_i32_e32 v91, 31, v90
	v_lshlrev_b64 v[84:85], 5, v[90:91]
	v_lshl_add_u64 v[84:85], v[140:141], 0, v[84:85]
	s_mov_b32 s26, 0x3d800000
	v_add_co_u32_e32 v84, vcc, 0x15b1d000, v84
	v_pk_mul_f32 v[94:95], v[94:95], s[26:27] op_sel_hi:[1,0]
	v_pk_mul_f32 v[92:93], v[92:93], s[26:27] op_sel_hi:[1,0]
	v_addc_co_u32_e32 v85, vcc, 0, v85, vcc
	global_store_dwordx4 v[84:85], v[92:95], off offset:3968

; DI void phaseA_tile(const P& p, int layer, int mt, int nt, char* lds) {
;     ...
;         const int lr = (half * 8 + pq) * 8 + wm * 4 + fq, row = row0 + lr;
;         const float r = rr[lr];
;         const float* tp = stg + lr * EPS + wn * 64;
;         const f32x4 v = *(const f32x4*)(tp + cc * 4) * r;
;         const f32x4 pv = *(const f32x4*)(tp + (cc ^ pair) * 4) * r;
;         const int bb = isS ? ((row - NTP) >> 6) : (row >> 11);
;         const int t = isS ? ((row - NTP) & 63) : (row & 2047);
;         f32x4 o;
;         o.x = v.x * c0[pq].x + sg * pv.x * c0[pq].y; o.y = v.y * c0[pq].z + sg * pv.y * c0[pq].w;
;         o.z = v.z * c1[pq].x + sg * pv.z * c1[pq].y; o.w = v.w * c1[pq].z + sg * pv.w * c1[pq].w;
.LBB0_1515:
	v_add_u32_e32 v0, 0x1080, v96
	v_add_u32_e32 v88, s57, v0
	v_lshl_add_u32 v0, v126, 2, v88
	s_waitcnt lgkmcnt(3)
	v_mov_b32_e32 v94, v194
	v_mov_b32_e32 v84, v50
	v_mov_b32_e32 v85, v51
	v_mov_b32_e32 v86, v52
	v_mov_b32_e32 v87, v53
	v_mov_b32_e32 v90, v54
	v_mov_b32_e32 v91, v55
	v_mov_b32_e32 v92, v56
	v_mov_b32_e32 v93, v57
	v_add_u32_e32 v0, v88, v155
	v_add_u32_e32 v0, 48, v156
	v_add_u32_e32 v82, s10, v0
	v_pk_mul_f32 v[84:85], v[84:85], v[94:95] op_sel_hi:[1,0]
	v_pk_mul_f32 v[86:87], v[86:87], v[94:95] op_sel_hi:[1,0]
	v_pk_mul_f32 v[90:91], v[90:91], v[94:95] op_sel_hi:[1,0]
	v_pk_mul_f32 v[92:93], v[92:93], v[94:95] op_sel_hi:[1,0]
	s_waitcnt vmcnt(2)
	v_mov_b32_e32 v95, v80
	v_pk_mul_f32 v[90:91], v[128:129], v[90:91]
	v_mov_b32_e32 v80, v79
	v_mov_b32_e32 v94, v78
	v_pk_mul_f32 v[78:79], v[80:81], v[90:91]
	v_mov_b32_e32 v81, v76
	v_pk_mul_f32 v[90:91], v[128:129], v[92:93]
	v_mov_b32_e32 v76, v75
	v_mov_b32_e32 v80, v74
	v_pk_mul_f32 v[74:75], v[76:77], v[90:91]
	v_pk_fma_f32 v[78:79], v[94:95], v[84:85], v[78:79]
	v_pk_fma_f32 v[80:81], v[80:81], v[86:87], v[74:75]
	s_and_b64 vcc, exec, s[46:47]
	s_mov_b64 s[0:1], -1
	s_cbranch_vccnz .LBB0_1547
	v_add_u32_e32 v74, 0xffff8000, v82
	v_ashrrev_i32_e32 v89, 6, v74
	v_ashrrev_i32_e32 v74, 11, v82
	v_and_b32_e32 v90, 63, v0
	v_and_b32_e32 v91, 0x7ff, v82
	s_and_b64 vcc, exec, s[44:45]
	s_cbranch_vccnz .LBB0_1536
	s_andn2_b64 vcc, exec, s[18:19]
	s_cbranch_vccnz .LBB0_1533
	s_and_saveexec_b64 s[0:1], s[40:41]
	s_xor_b64 s[0:1], exec, s[0:1]
	s_cbranch_execz .LBB0_1522
	s_and_saveexec_b64 s[24:25], s[42:43]
	s_cbranch_execz .LBB0_1521
	v_ashrrev_i32_e32 v83, 31, v82
	v_lshlrev_b64 v[76:77], 5, v[82:83]
	v_lshl_add_u64 v[76:77], v[140:141], 0, v[76:77]
	s_mov_b32 s26, 0x3d800000
	v_add_co_u32_e32 v76, vcc, 0x15b1d000, v76
	v_pk_mul_f32 v[86:87], v[86:87], s[26:27] op_sel_hi:[1,0]
	v_pk_mul_f32 v[84:85], v[84:85], s[26:27] op_sel_hi:[1,0]
	v_addc_co_u32_e32 v77, vcc, 0, v77, vcc
	global_store_dwordx4 v[76:77], v[84:87], off offset:3968

; DI void phaseA_tile(const P& p, int layer, int mt, int nt, char* lds) {
;     ...
;         const int lr = (half * 8 + pq) * 8 + wm * 4 + fq, row = row0 + lr;
;         const float r = rr[lr];
;         const float* tp = stg + lr * EPS + wn * 64;
;         const f32x4 v = *(const f32x4*)(tp + cc * 4) * r;
;         const f32x4 pv = *(const f32x4*)(tp + (cc ^ pair) * 4) * r;
;         const int bb = isS ? ((row - NTP) >> 6) : (row >> 11);
;         const int t = isS ? ((row - NTP) & 63) : (row & 2047);
;         f32x4 o;
;         o.x = v.x * c0[pq].x + sg * pv.x * c0[pq].y; o.y = v.y * c0[pq].z + sg * pv.y * c0[pq].w;
;         o.z = v.z * c1[pq].x + sg * pv.z * c1[pq].y; o.w = v.w * c1[pq].z + sg * pv.w * c1[pq].w;
.LBB0_1549:
	v_add_u32_e32 v0, 0x1080, v88
	v_lshl_add_u32 v74, v126, 2, v0
	v_add_u32_e32 v0, v0, v155
	s_waitcnt lgkmcnt(0)
	v_mov_b32_e32 v84, v195
	v_mov_b32_e32 v76, v58
	v_mov_b32_e32 v77, v59
	v_mov_b32_e32 v78, v60
	v_mov_b32_e32 v79, v61
	v_mov_b32_e32 v80, v62
	v_mov_b32_e32 v81, v63
	v_mov_b32_e32 v82, v64
	v_mov_b32_e32 v83, v65
	v_add_u32_e32 v0, 56, v156
	v_add_u32_e32 v74, s10, v0
	s_and_b64 vcc, exec, s[46:47]
	v_pk_mul_f32 v[76:77], v[76:77], v[84:85] op_sel_hi:[1,0]
	v_pk_mul_f32 v[80:81], v[80:81], v[84:85] op_sel_hi:[1,0]
	v_pk_mul_f32 v[78:79], v[78:79], v[84:85] op_sel_hi:[1,0]
	v_pk_mul_f32 v[82:83], v[82:83], v[84:85] op_sel_hi:[1,0]
	s_waitcnt vmcnt(0)
	v_mov_b32_e32 v85, v72
	v_pk_mul_f32 v[80:81], v[128:129], v[80:81]
	v_mov_b32_e32 v72, v71
	v_mov_b32_e32 v84, v70
	v_pk_mul_f32 v[70:71], v[72:73], v[80:81]
	v_mov_b32_e32 v73, v68
	v_pk_mul_f32 v[80:81], v[128:129], v[82:83]
	v_mov_b32_e32 v68, v67
	v_mov_b32_e32 v72, v66
	v_pk_mul_f32 v[66:67], v[68:69], v[80:81]
	v_pk_fma_f32 v[70:71], v[84:85], v[76:77], v[70:71]
	v_pk_fma_f32 v[72:73], v[72:73], v[78:79], v[66:67]
	s_mov_b64 s[0:1], -1
	v_readlane_b32 s46, v238, 49
	v_readlane_b32 s47, v238, 50
	s_cbranch_vccnz .LBB0_1581
	v_add_u32_e32 v66, 0xffff8000, v74
	v_ashrrev_i32_e32 v80, 6, v66
	v_ashrrev_i32_e32 v66, 11, v74
	v_and_b32_e32 v81, 63, v0
	v_and_b32_e32 v82, 0x7ff, v74
	s_and_b64 vcc, exec, s[44:45]
	s_cbranch_vccnz .LBB0_1570
	s_andn2_b64 vcc, exec, s[18:19]
	s_cbranch_vccnz .LBB0_1567
	s_and_saveexec_b64 s[0:1], s[40:41]
	s_xor_b64 s[0:1], exec, s[0:1]
	s_cbranch_execz .LBB0_1556
	s_and_saveexec_b64 s[24:25], s[42:43]
	s_cbranch_execz .LBB0_1555
	v_ashrrev_i32_e32 v75, 31, v74
	v_lshlrev_b64 v[68:69], 5, v[74:75]
	v_lshl_add_u64 v[68:69], v[140:141], 0, v[68:69]
	s_mov_b32 s26, 0x3d800000
	v_add_co_u32_e32 v68, vcc, 0x15b1d000, v68
	v_pk_mul_f32 v[78:79], v[78:79], s[26:27] op_sel_hi:[1,0]
	v_pk_mul_f32 v[76:77], v[76:77], s[26:27] op_sel_hi:[1,0]
	v_addc_co_u32_e32 v69, vcc, 0, v69, vcc
	global_store_dwordx4 v[68:69], v[76:79], off offset:3968
